# dil PV: first three V fragments prefetched into the dead K-fragment registers right after QK^T, remaining five tr-reads issued together after the P conversions with counted lgkmcnt waits
# speedup vs baseline: 1.0061x; 1.0043x over previous
; #define LAS __attribute__((address_space(3)))
; #define MFMA32(a, b, c) __builtin_amdgcn_mfma_f32_32x32x16_bf16((a), (b), (c), 0, 0, 0)
; __device__ __forceinline__ int crow(int i, int h) { return (i & 3) + 8 * (i >> 2) + 4 * h; }
; template <int MODE, class SF> ...
;     ...
; #pragma unroll
;     for (int s = 0; s < 4; ++s) { ka[s] = *(LAS const bf16x8*)(ksb + r * KSB + (16 * s + 8 * hh) * 2); kb2[s] = *(LAS const bf16x8*)(ksb + (32 + r) * KSB + (16 * s + 8 * hh) * 2); }
;     __builtin_amdgcn_s_setprio(1);
; #pragma unroll
;     for (int s = 0; s < 4; ++s) { s0 = MFMA32(ka[s], qf[s], s0); s1 = MFMA32(kb2[s], qf[s], s1); }
;     __builtin_amdgcn_s_setprio(0);
;     __builtin_amdgcn_sched_barrier(0);
; #pragma unroll
;     for (int i = 0; i < 16; ++i) { s0[i] = sf(s0[i], crow(i, hh)); s1[i] = sf(s1[i], 32 + crow(i, hh)); }
.LBB0_867:
	s_add_i32 s0, s43, 63
	s_cmp_lt_i32 s0, s7
	s_cselect_b64 s[0:1], -1, 0
	s_cmp_gt_i32 s43, s8
	s_cselect_b64 s[26:27], -1, 0
	s_or_b64 s[0:1], s[0:1], s[26:27]
	s_and_b64 vcc, exec, s[0:1]
	s_cbranch_vccnz .LBB0_871
	v_add3_u32 v56, s16, v111, v0
	ds_read_b128 v[48:51], v56
	ds_read_b128 v[116:119], v56 offset:32
	ds_read_b128 v[52:55], v56 offset:4608
	ds_read_b128 v[120:123], v56 offset:4640
	ds_read_b128 v[190:193], v56 offset:64
	ds_read_b128 v[194:197], v56 offset:96
	ds_read_b128 v[198:201], v56 offset:4672
	ds_read_b128 v[202:205], v56 offset:4704
	s_setprio 1
	s_waitcnt lgkmcnt(7)
	v_mfma_f32_32x32x16_bf16 v[64:79], v[48:51], v[88:91], 0
	s_waitcnt lgkmcnt(5)
	v_mfma_f32_32x32x16_bf16 v[48:63], v[52:55], v[88:91], 0
	v_mfma_f32_32x32x16_bf16 v[64:79], v[116:119], v[84:87], v[64:79]
	s_waitcnt lgkmcnt(4)
	v_mfma_f32_32x32x16_bf16 v[48:63], v[120:123], v[84:87], v[48:63]
	s_waitcnt lgkmcnt(3)
	v_mfma_f32_32x32x16_bf16 v[64:79], v[190:193], v[80:83], v[64:79]
	s_waitcnt lgkmcnt(1)
	v_mfma_f32_32x32x16_bf16 v[48:63], v[198:201], v[80:83], v[48:63]
	v_mfma_f32_32x32x16_bf16 v[64:79], v[194:197], v[10:13], v[64:79]
	s_waitcnt lgkmcnt(0)
	v_mfma_f32_32x32x16_bf16 v[48:63], v[202:205], v[10:13], v[48:63]
	s_setprio 0
	v_add_u32_e32 v190, s98, v112
	ds_read_b64_tr_b16 v[194:195], v190 offset:18432
	ds_read_b64_tr_b16 v[196:197], v190 offset:19968
	ds_read_b64_tr_b16 v[198:199], v190 offset:18496
	ds_read_b64_tr_b16 v[200:201], v190 offset:20032
	ds_read_b64_tr_b16 v[202:203], v190 offset:21504
	ds_read_b64_tr_b16 v[204:205], v190 offset:23040
	v_add_u32_e32 v116, 27, v113
	v_cvt_f32_u32_e32 v117, v116
	v_add_u32_e32 v118, -5, v113
	v_cvt_f32_u32_e32 v119, v118
	v_cmp_gt_u32_e32 vcc, s33, v116
	s_nop 3
	v_fma_f32 v64, -v93, v117, v64
	v_add_u32_e32 v116, 26, v113
	v_cndmask_b32_e32 v64, v215, v64, vcc
	v_cvt_f32_u32_e32 v117, v116
	v_cmp_gt_u32_e32 vcc, s33, v118
	v_add_u32_e32 v118, -6, v113
	v_fma_f32 v48, -v93, v119, v48
	v_cvt_f32_u32_e32 v119, v118
	v_cndmask_b32_e32 v48, v215, v48, vcc
	v_fma_f32 v65, -v93, v117, v65
	v_cmp_gt_u32_e32 vcc, s33, v116
	v_fma_f32 v49, -v93, v119, v49
	v_add_u32_e32 v116, 25, v113
	v_cndmask_b32_e32 v65, v215, v65, vcc
	v_cmp_gt_u32_e32 vcc, s33, v118
	v_cvt_f32_u32_e32 v117, v116
	v_fma_f32 v66, -v93, v117, v66
	v_cndmask_b32_e32 v118, v215, v49, vcc
	v_add_u32_e32 v49, -7, v113
	v_cvt_f32_u32_e32 v119, v49
	v_cmp_gt_u32_e32 vcc, s33, v116
	v_add_u32_e32 v116, 24, v113
	v_cvt_f32_u32_e32 v117, v116
	v_cndmask_b32_e32 v66, v215, v66, vcc
	v_fma_f32 v50, -v93, v119, v50
	v_cmp_gt_u32_e32 vcc, s33, v49
	v_add_u32_e32 v49, -8, v113
	v_fma_f32 v67, -v93, v117, v67
	v_cndmask_b32_e32 v119, v215, v50, vcc
	v_cvt_f32_u32_e32 v50, v49
	v_cmp_gt_u32_e32 vcc, s33, v116
	v_fma_f32 v50, -v93, v50, v51
	v_add_u32_e32 v51, 19, v113
	v_cndmask_b32_e32 v67, v215, v67, vcc
	v_cvt_f32_u32_e32 v116, v51
	v_cmp_gt_u32_e32 vcc, s33, v49
	v_add_u32_e32 v49, -13, v113
	v_fma_f32 v68, -v93, v116, v68
	v_cndmask_b32_e32 v117, v215, v50, vcc
	v_cvt_f32_u32_e32 v50, v49
	v_cmp_gt_u32_e32 vcc, s33, v51
	v_add_u32_e32 v51, 18, v113
	v_fma_f32 v50, -v93, v50, v52
	v_cndmask_b32_e32 v116, v215, v68, vcc
	v_cvt_f32_u32_e32 v52, v51
	v_cmp_gt_u32_e32 vcc, s33, v49
	v_add_u32_e32 v49, -14, v113
	v_fma_f32 v52, -v93, v52, v69
	v_cndmask_b32_e32 v120, v215, v50, vcc
	v_cvt_f32_u32_e32 v50, v49
	v_cmp_gt_u32_e32 vcc, s33, v51
	v_add_u32_e32 v51, 17, v113
	v_fma_f32 v50, -v93, v50, v53
	v_cndmask_b32_e32 v69, v215, v52, vcc
	v_cvt_f32_u32_e32 v52, v51
	v_cmp_gt_u32_e32 vcc, s33, v49
	v_add_u32_e32 v49, -15, v113
	v_fma_f32 v52, -v93, v52, v70
	v_cndmask_b32_e32 v121, v215, v50, vcc
	v_cvt_f32_u32_e32 v50, v49
	v_cmp_gt_u32_e32 vcc, s33, v51
	v_add_u32_e32 v51, 16, v113
	v_fma_f32 v50, -v93, v50, v54
	v_cndmask_b32_e32 v122, v215, v52, vcc
	v_cvt_f32_u32_e32 v52, v51
	v_cmp_gt_u32_e32 vcc, s33, v49
	v_add_u32_e32 v49, -16, v113
	v_fma_f32 v52, -v93, v52, v71
	v_cndmask_b32_e32 v123, v215, v50, vcc
	v_cvt_f32_u32_e32 v50, v49
	v_cmp_gt_u32_e32 vcc, s33, v51
	v_add_u32_e32 v51, 11, v113
	v_fma_f32 v50, -v93, v50, v55
	v_cndmask_b32_e32 v71, v215, v52, vcc
	v_cvt_f32_u32_e32 v52, v51
	v_cmp_gt_u32_e32 vcc, s33, v49
	v_subrev_u32_e32 v49, 21, v113
	v_fma_f32 v52, -v93, v52, v72
	v_cndmask_b32_e32 v55, v215, v50, vcc
	v_cvt_f32_u32_e32 v50, v49
	v_cmp_gt_u32_e32 vcc, s33, v51
	v_add_u32_e32 v51, 10, v113
	v_fma_f32 v50, -v93, v50, v56
	v_cndmask_b32_e32 v140, v215, v52, vcc
	v_cvt_f32_u32_e32 v52, v51
	v_cmp_gt_u32_e32 vcc, s33, v49
	v_subrev_u32_e32 v49, 22, v113
	v_fma_f32 v52, -v93, v52, v73
	v_cndmask_b32_e32 v141, v215, v50, vcc
	v_cvt_f32_u32_e32 v50, v49
	v_cmp_gt_u32_e32 vcc, s33, v51
	v_add_u32_e32 v51, 9, v113
	v_fma_f32 v50, -v93, v50, v57
	v_cndmask_b32_e32 v73, v215, v52, vcc
	v_cvt_f32_u32_e32 v52, v51
	v_cmp_gt_u32_e32 vcc, s33, v49
	v_subrev_u32_e32 v49, 23, v113
	v_fma_f32 v52, -v93, v52, v74
	v_cndmask_b32_e32 v57, v215, v50, vcc
	v_cvt_f32_u32_e32 v50, v49
	v_cmp_gt_u32_e32 vcc, s33, v51
	v_add_u32_e32 v51, 8, v113
	v_fma_f32 v50, -v93, v50, v58
	v_cndmask_b32_e32 v146, v215, v52, vcc
	v_cvt_f32_u32_e32 v52, v51
	v_cmp_gt_u32_e32 vcc, s33, v49
	v_subrev_u32_e32 v49, 24, v113
	v_fma_f32 v52, -v93, v52, v75
	v_cndmask_b32_e32 v147, v215, v50, vcc
	v_cvt_f32_u32_e32 v50, v49
	v_cmp_gt_u32_e32 vcc, s33, v51
	v_add_u32_e32 v51, 3, v113
	v_fma_f32 v50, -v93, v50, v59
	v_cndmask_b32_e32 v165, v215, v52, vcc
	v_cvt_f32_u32_e32 v52, v51
	v_cmp_gt_u32_e32 vcc, s33, v49
	v_subrev_u32_e32 v49, 29, v113
	v_fma_f32 v52, -v93, v52, v76
	v_cndmask_b32_e32 v167, v215, v50, vcc
	v_cvt_f32_u32_e32 v50, v49
	v_cmp_gt_u32_e32 vcc, s33, v51
; __device__ __forceinline__ float sum32(float v) { auto rr = __builtin_amdgcn_permlane32_swap(__float_as_uint(v), __float_as_uint(v), false, false); return __uint_as_float(rr[0]) + __uint_as_float(rr[1]); }
; __device__ __forceinline__ float max32(float v) { auto rr = __builtin_amdgcn_permlane32_swap(__float_as_uint(v), __float_as_uint(v), false, false); return fmaxf(__uint_as_float(rr[0]), __uint_as_float(rr[1])); }
; #define EXP2(x) __builtin_amdgcn_exp2f(x)
; template <int MODE, class SF> ...
;     ...
;     if (MODE != 2) {
;         float mloc = fmaxf(s0[0], s1[0]);
; #pragma unroll
;         for (int i = 1; i < 16; ++i) mloc = fmaxf(mloc, fmaxf(s0[i], s1[i]));
;         mloc = max32(mloc);
;         const float mnew = fmaxf(m, mloc), msafe = mnew == -INFINITY ? 0.f : mnew, corr = EXP2(m - msafe);
;         float psum = 0.f;
; #pragma unroll
;         for (int i = 0; i < 16; ++i) { s0[i] = EXP2(s0[i] - msafe); s1[i] = EXP2(s1[i] - msafe); psum += s0[i] + s1[i]; }
;         psum = sum32(psum);
;         l = l * corr + psum; m = mnew;
;         if (MODE == 0 && !__all(corr == 1.f)) {
; #pragma unroll
;             for (int i = 0; i < 16; ++i) { o0[i] *= corr; o1[i] *= corr; } }
	v_add_u32_e32 v51, 2, v113
	v_fma_f32 v50, -v93, v50, v60
	v_cndmask_b32_e32 v169, v215, v52, vcc
	v_cvt_f32_u32_e32 v52, v51
	v_cmp_gt_u32_e32 vcc, s33, v49
	v_subrev_u32_e32 v49, 30, v113
	v_fma_f32 v52, -v93, v52, v77
	v_cndmask_b32_e32 v171, v215, v50, vcc
	v_cvt_f32_u32_e32 v50, v49
	v_cmp_gt_u32_e32 vcc, s33, v51
	v_add_u32_e32 v51, 1, v113
	v_fma_f32 v50, -v93, v50, v61
	v_cndmask_b32_e32 v173, v215, v52, vcc
	v_cvt_f32_u32_e32 v52, v51
	v_cmp_gt_u32_e32 vcc, s33, v49
	v_subrev_u32_e32 v49, 31, v113
	v_fma_f32 v52, -v93, v52, v78
	v_cndmask_b32_e32 v175, v215, v50, vcc
	v_cvt_f32_u32_e32 v50, v49
	v_cmp_gt_u32_e32 vcc, s33, v51
	v_cvt_f32_u32_e32 v51, v113
	v_fma_f32 v50, -v93, v50, v62
	v_cndmask_b32_e32 v177, v215, v52, vcc
	v_cmp_gt_u32_e32 vcc, s33, v49
	v_subrev_u32_e32 v49, 32, v113
	v_fma_f32 v51, -v93, v51, v79
	v_cndmask_b32_e32 v179, v215, v50, vcc
	v_cvt_f32_u32_e32 v50, v49
	v_cmp_gt_u32_e32 vcc, s33, v113
	v_fma_f32 v50, -v93, v50, v63
	s_nop 0
	v_cndmask_b32_e32 v181, v215, v51, vcc
	v_cmp_gt_u32_e32 vcc, s33, v49
	v_max_f32_e32 v49, v65, v118
	v_max3_f32 v49, v64, v48, v49
	v_cndmask_b32_e32 v183, v215, v50, vcc
	v_max_f32_e32 v50, v66, v119
	v_max_f32_e32 v51, v67, v117
	v_max3_f32 v49, v49, v50, v51
	v_max_f32_e32 v50, v116, v120
	v_max_f32_e32 v51, v69, v121
	v_max3_f32 v49, v49, v50, v51
	v_max_f32_e32 v50, v122, v123
	v_max_f32_e32 v51, v71, v55
	v_max3_f32 v49, v49, v50, v51
	v_max_f32_e32 v50, v140, v141
	v_max_f32_e32 v51, v73, v57
	v_max3_f32 v49, v49, v50, v51
	v_max_f32_e32 v50, v146, v147
	v_max_f32_e32 v51, v165, v167
	v_max3_f32 v49, v49, v50, v51
	v_max_f32_e32 v50, v169, v171
	v_max_f32_e32 v51, v173, v175
	v_max3_f32 v49, v49, v50, v51
	v_max_f32_e32 v50, v177, v179
	v_max_f32_e32 v51, v181, v183
	v_max3_f32 v49, v49, v50, v51
	v_mov_b32_e32 v50, v49
	s_nop 1
	v_permlane32_swap_b32_e32 v49, v50
	v_max3_f32 v49, v115, v49, v50
	v_cmp_neq_f32_e32 vcc, s34, v49
	s_nop 1
	v_cndmask_b32_e32 v185, 0, v49, vcc
	v_sub_f32_e32 v50, v64, v185
	v_sub_f32_e32 v48, v48, v185
	v_exp_f32_e32 v62, v50
	v_exp_f32_e32 v50, v48
	v_sub_f32_e32 v48, v65, v185
	v_exp_f32_e32 v64, v48
	v_sub_f32_e32 v48, v118, v185
	v_add_f32_e32 v52, v62, v50
	v_add_f32_e32 v54, 0, v52
	v_sub_f32_e32 v52, v66, v185
	v_exp_f32_e32 v51, v48
	v_exp_f32_e32 v66, v52
	v_sub_f32_e32 v52, v119, v185
	v_exp_f32_e32 v52, v52
	v_add_f32_e32 v56, v64, v51
	v_sub_f32_e32 v53, v67, v185
	v_add_f32_e32 v54, v56, v54
	v_add_f32_e32 v56, v66, v52
	v_exp_f32_e32 v68, v53
	v_sub_f32_e32 v53, v117, v185
	v_add_f32_e32 v58, v56, v54
	v_sub_f32_e32 v54, v116, v185
	v_exp_f32_e32 v53, v53
	v_exp_f32_e32 v70, v54
	v_sub_f32_e32 v54, v120, v185
	v_exp_f32_e32 v54, v54
	v_add_f32_e32 v59, v68, v53
	v_sub_f32_e32 v56, v69, v185
	v_add_f32_e32 v58, v59, v58
	v_add_f32_e32 v59, v70, v54
	v_exp_f32_e32 v72, v56
	v_sub_f32_e32 v56, v121, v185
	v_add_f32_e32 v59, v59, v58
	v_sub_f32_e32 v58, v122, v185
	v_exp_f32_e32 v56, v56
	v_exp_f32_e32 v74, v58
	v_sub_f32_e32 v58, v123, v185
	v_exp_f32_e32 v58, v58
	v_add_f32_e32 v61, v72, v56
	v_sub_f32_e32 v60, v71, v185
	v_sub_f32_e32 v55, v55, v185
	v_exp_f32_e32 v76, v60
	v_exp_f32_e32 v60, v55
	v_add_f32_e32 v55, v61, v59
	v_add_f32_e32 v59, v74, v58
	v_add_f32_e32 v59, v59, v55
	v_sub_f32_e32 v55, v140, v185
	v_exp_f32_e32 v71, v55
	v_sub_f32_e32 v55, v141, v185
	v_exp_f32_e32 v55, v55
	v_add_f32_e32 v61, v76, v60
	v_sub_f32_e32 v63, v73, v185
	v_add_f32_e32 v59, v61, v59
	v_add_f32_e32 v61, v71, v55
	v_exp_f32_e32 v73, v63
	v_sub_f32_e32 v57, v57, v185
	v_add_f32_e32 v63, v61, v59
	v_sub_f32_e32 v59, v146, v185
	v_exp_f32_e32 v57, v57
	v_exp_f32_e32 v75, v59
	v_sub_f32_e32 v59, v147, v185
	v_exp_f32_e32 v59, v59
	v_add_f32_e32 v65, v73, v57
	v_sub_f32_e32 v61, v165, v185
	v_add_f32_e32 v63, v65, v63
	v_add_f32_e32 v65, v75, v59
	v_exp_f32_e32 v77, v61
	v_sub_f32_e32 v61, v167, v185
	v_add_f32_e32 v67, v65, v63
	v_sub_f32_e32 v63, v169, v185
	v_exp_f32_e32 v61, v61
	v_exp_f32_e32 v78, v63
	v_sub_f32_e32 v63, v171, v185
	v_sub_f32_e32 v65, v173, v185
	v_exp_f32_e32 v63, v63
	v_exp_f32_e32 v79, v65
	v_sub_f32_e32 v65, v175, v185
	v_exp_f32_e32 v65, v65
	v_add_f32_e32 v69, v77, v61
	v_add_f32_e32 v67, v69, v67
	v_add_f32_e32 v69, v78, v63
	v_add_f32_e32 v67, v69, v67
	v_add_f32_e32 v69, v79, v65
	v_add_f32_e32 v117, v69, v67
	v_sub_f32_e32 v67, v177, v185
	v_sub_f32_e32 v48, v115, v185
	v_exp_f32_e32 v115, v67
	v_sub_f32_e32 v67, v179, v185
	v_sub_f32_e32 v69, v181, v185
	v_exp_f32_e32 v67, v67
	v_exp_f32_e32 v116, v69
	v_sub_f32_e32 v69, v183, v185
	v_exp_f32_e32 v69, v69
	v_exp_f32_e32 v48, v48
	v_add_f32_e32 v118, v115, v67
	v_add_f32_e32 v117, v118, v117
	v_add_f32_e32 v118, v116, v69
	v_add_f32_e32 v117, v118, v117
	v_mov_b32_e32 v118, v117
	v_cmp_eq_f32_e32 vcc, 1.0, v48
	s_cmp_eq_u64 vcc, exec
	v_permlane32_swap_b32_e32 v117, v118
	s_cbranch_scc1 .LBB0_870
	v_pk_mul_f32 v[30:31], v[30:31], v[48:49] op_sel_hi:[1,0]
	v_pk_mul_f32 v[28:29], v[28:29], v[48:49] op_sel_hi:[1,0]
	v_pk_mul_f32 v[26:27], v[26:27], v[48:49] op_sel_hi:[1,0]
	v_pk_mul_f32 v[24:25], v[24:25], v[48:49] op_sel_hi:[1,0]
	v_pk_mul_f32 v[22:23], v[22:23], v[48:49] op_sel_hi:[1,0]
	v_pk_mul_f32 v[20:21], v[20:21], v[48:49] op_sel_hi:[1,0]
	v_pk_mul_f32 v[18:19], v[18:19], v[48:49] op_sel_hi:[1,0]
	v_pk_mul_f32 v[16:17], v[16:17], v[48:49] op_sel_hi:[1,0]
	v_pk_mul_f32 v[46:47], v[46:47], v[48:49] op_sel_hi:[1,0]
	v_pk_mul_f32 v[44:45], v[44:45], v[48:49] op_sel_hi:[1,0]
	v_pk_mul_f32 v[42:43], v[42:43], v[48:49] op_sel_hi:[1,0]
	v_pk_mul_f32 v[40:41], v[40:41], v[48:49] op_sel_hi:[1,0]
	v_pk_mul_f32 v[38:39], v[38:39], v[48:49] op_sel_hi:[1,0]
	v_pk_mul_f32 v[36:37], v[36:37], v[48:49] op_sel_hi:[1,0]
	v_pk_mul_f32 v[34:35], v[34:35], v[48:49] op_sel_hi:[1,0]
	v_pk_mul_f32 v[32:33], v[32:33], v[48:49] op_sel_hi:[1,0]
; #define LAS __attribute__((address_space(3)))
; __device__ __forceinline__ unsigned cvtpk(float lo, float hi) { f32x2_t v = {lo, hi}; bf16x2_t b = __builtin_convertvector(v, bf16x2_t); return __builtin_bit_cast(unsigned, b); }
; #define MFMA32(a, b, c) __builtin_amdgcn_mfma_f32_32x32x16_bf16((a), (b), (c), 0, 0, 0)
; __device__ __forceinline__ void pv_accum(const f32x16& s0, const f32x16& s1, f32x16& o0, f32x16& o1, LAS const unsigned char* vtb, int r, int hh) {
;     __builtin_amdgcn_s_setprio(1);
; #pragma unroll
;     for (int kt = 0; kt < 2; ++kt)
; #pragma unroll
;         for (int sp = 0; sp < 2; ++sp) { u32x4 w;
;             if (kt == 0) { w.x = cvtpk(s0[8 * sp], s0[8 * sp + 1]); w.y = cvtpk(s0[8 * sp + 2], s0[8 * sp + 3]); w.z = cvtpk(s0[8 * sp + 4], s0[8 * sp + 5]); w.w = cvtpk(s0[8 * sp + 6], s0[8 * sp + 7]); }
;             else         { w.x = cvtpk(s1[8 * sp], s1[8 * sp + 1]); w.y = cvtpk(s1[8 * sp + 2], s1[8 * sp + 3]); w.z = cvtpk(s1[8 * sp + 4], s1[8 * sp + 5]); w.w = cvtpk(s1[8 * sp + 6], s1[8 * sp + 7]); }
;             const bf16x8 pb = __builtin_bit_cast(bf16x8, w); const int ko = 32 * kt + 16 * sp + 4 * hh;
;             { const s16x4 lo = *(LAS const s16x4*)(vtb + r * VTB + ko * 2), hi = *(LAS const s16x4*)(vtb + r * VTB + (ko + 8) * 2);
;               o0 = MFMA32(__builtin_shufflevector(lo, hi, 0, 1, 2, 3, 4, 5, 6, 7), pb, o0); }
;             { const s16x4 lo = *(LAS const s16x4*)(vtb + (32 + r) * VTB + ko * 2), hi = *(LAS const s16x4*)(vtb + (32 + r) * VTB + (ko + 8) * 2);
;               o1 = MFMA32(__builtin_shufflevector(lo, hi, 0, 1, 2, 3, 4, 5, 6, 7), pb, o1); } }
;     __builtin_amdgcn_s_setprio(0);
.LBB0_870:
	v_add_f32_e32 v117, v117, v118
	v_fmac_f32_e32 v117, v107, v48
	s_setprio 1
	v_cvt_pk_bf16_f32 v118, v62, v64
	v_cvt_pk_bf16_f32 v119, v66, v68
	v_cvt_pk_bf16_f32 v120, v70, v72
	v_cvt_pk_bf16_f32 v121, v74, v76
	s_nop 0
	v_cvt_pk_bf16_f32 v70, v71, v73
	v_cvt_pk_bf16_f32 v71, v75, v77
	v_cvt_pk_bf16_f32 v72, v78, v79
	v_cvt_pk_bf16_f32 v73, v115, v116
	v_cvt_pk_bf16_f32 v50, v50, v51
	v_cvt_pk_bf16_f32 v51, v52, v53
	v_cvt_pk_bf16_f32 v52, v54, v56
	v_cvt_pk_bf16_f32 v53, v58, v60
	v_cvt_pk_bf16_f32 v54, v55, v57
	v_cvt_pk_bf16_f32 v55, v59, v61
	v_cvt_pk_bf16_f32 v56, v63, v65
	v_cvt_pk_bf16_f32 v57, v67, v69
	ds_read_b64_tr_b16 v[74:75], v190 offset:21568
	ds_read_b64_tr_b16 v[76:77], v190 offset:23104
	ds_read_b64_tr_b16 v[58:59], v190 offset:24576
	ds_read_b64_tr_b16 v[60:61], v190 offset:26112
	ds_read_b64_tr_b16 v[62:63], v190 offset:24640
	ds_read_b64_tr_b16 v[64:65], v190 offset:26176
	ds_read_b64_tr_b16 v[66:67], v190 offset:27648
	ds_read_b64_tr_b16 v[68:69], v190 offset:29184
	s_waitcnt lgkmcnt(8)
	v_mfma_f32_32x32x16_bf16 v[16:31], v[194:197], v[118:121], v[16:31]
	v_mfma_f32_32x32x16_bf16 v[32:47], v[198:201], v[118:121], v[32:47]
	ds_read_b64_tr_b16 v[194:195], v190 offset:27712
	ds_read_b64_tr_b16 v[196:197], v190 offset:29248
	v_mfma_f32_32x32x16_bf16 v[16:31], v[202:205], v[70:73], v[16:31]
	s_waitcnt lgkmcnt(8)
	v_mfma_f32_32x32x16_bf16 v[32:47], v[74:77], v[70:73], v[32:47]
	s_waitcnt lgkmcnt(6)
	v_mfma_f32_32x32x16_bf16 v[16:31], v[58:61], v[50:53], v[16:31]
	s_waitcnt lgkmcnt(4)
	v_mfma_f32_32x32x16_bf16 v[32:47], v[62:65], v[50:53], v[32:47]
	s_waitcnt lgkmcnt(2)
	v_mfma_f32_32x32x16_bf16 v[16:31], v[66:69], v[54:57], v[16:31]
	s_waitcnt lgkmcnt(0)
	v_mfma_f32_32x32x16_bf16 v[32:47], v[194:197], v[54:57], v[32:47]
	s_setprio 0
	v_mov_b32_e32 v107, v117
	s_branch .LBB0_872
